# D + modulate k0/k3 row loops: next-row prefetch no longer drained by vmcnt(0) at loop top (counted waits)
# baseline (speedup 1.0000x reference)
; #define GAS __attribute__((address_space(1)))
; __device__ __forceinline__ unsigned pk2(float lo, float hi) { return f2bf(lo) | (f2bf(hi) << 16); }
; __device__ __forceinline__ void modulate_phase(Frame& F, const float* x, bf16* H, const float* gnorm, const float* modsub) {
;     ...
;         float s = 0.f;
; #pragma unroll
;         for (int j = 0; j < 8; ++j) s += (v[j].x * v[j].x + v[j].y * v[j].y) + (v[j].z * v[j].z + v[j].w * v[j].w);
;         const float rstd = 1.0f / sqrtf(wave_sum(s) * (1.0f / D) + RMS_EPS);
;         GAS unsigned long long* o8 = (GAS unsigned long long*)(H + (size_t)r * D) + F.lane;
; #pragma unroll
;         for (int j = 0; j < 8; ++j) { const f32x4 y = v[j] * rstd * gs[j] + sh[j];
;             o8[64 * j] = (unsigned long long)pk2(y.x, y.y) | ((unsigned long long)pk2(y.z, y.w) << 32); }
.LBB0_216:
	s_waitcnt vmcnt(8)
	v_mul_f32_e32 v0, v95, v95
	v_mul_f32_e32 v149, v97, v97
	v_fmac_f32_e32 v0, v94, v94
	v_fmac_f32_e32 v149, v96, v96
	v_add_f32_e32 v0, v0, v149
	v_mul_f32_e32 v149, v91, v91
	v_mul_f32_e32 v150, v93, v93
	v_fmac_f32_e32 v149, v90, v90
	v_fmac_f32_e32 v150, v92, v92
	v_add_f32_e32 v149, v149, v150
	v_add_f32_e32 v0, v0, v149
	v_mul_f32_e32 v149, v55, v55
	v_mul_f32_e32 v150, v57, v57
	v_fmac_f32_e32 v149, v54, v54
	v_fmac_f32_e32 v150, v56, v56
	v_add_f32_e32 v149, v149, v150
	v_add_f32_e32 v0, v149, v0
	v_mul_f32_e32 v149, v43, v43
	v_mul_f32_e32 v150, v45, v45
	v_fmac_f32_e32 v149, v42, v42
	v_fmac_f32_e32 v150, v44, v44
	v_add_f32_e32 v149, v149, v150
	v_add_f32_e32 v0, v149, v0
	v_mul_f32_e32 v149, v31, v31
	v_mul_f32_e32 v150, v33, v33
	v_fmac_f32_e32 v149, v30, v30
	v_fmac_f32_e32 v150, v32, v32
	v_add_f32_e32 v149, v149, v150
	v_add_f32_e32 v0, v149, v0
	v_mul_f32_e32 v149, v27, v27
	v_mul_f32_e32 v150, v29, v29
	v_fmac_f32_e32 v149, v26, v26
	v_fmac_f32_e32 v150, v28, v28
	v_add_f32_e32 v149, v149, v150
	v_add_f32_e32 v0, v149, v0
	v_mul_f32_e32 v149, v15, v15
	v_mul_f32_e32 v150, v17, v17
	v_fmac_f32_e32 v149, v14, v14
	v_fmac_f32_e32 v150, v16, v16
	v_add_f32_e32 v149, v149, v150
	v_add_f32_e32 v0, v149, v0
	v_mul_f32_e32 v149, v11, v11
	v_mul_f32_e32 v150, v13, v13
	v_fmac_f32_e32 v149, v10, v10
	v_fmac_f32_e32 v150, v12, v12
	v_add_f32_e32 v149, v149, v150
	v_add_f32_e32 v0, v149, v0
	ds_swizzle_b32 v149, v0 offset:swizzle(SWAP,1)
	s_waitcnt lgkmcnt(0)
	v_add_f32_e32 v0, v0, v149
	ds_swizzle_b32 v149, v0 offset:swizzle(SWAP,2)
	s_waitcnt lgkmcnt(0)
	v_add_f32_e32 v0, v0, v149
	ds_swizzle_b32 v149, v0 offset:swizzle(SWAP,4)
	s_waitcnt lgkmcnt(0)
	v_add_f32_e32 v0, v0, v149
	ds_swizzle_b32 v149, v0 offset:swizzle(SWAP,8)
	s_waitcnt lgkmcnt(0)
	v_add_f32_e32 v0, v0, v149
	ds_swizzle_b32 v149, v0 offset:swizzle(SWAP,16)
	s_waitcnt lgkmcnt(0)
	v_add_f32_e32 v0, v0, v149
	v_mov_b32_e32 v149, v0
	s_nop 1
	v_permlane32_swap_b32_e32 v0, v149
	v_add_f32_e32 v0, v0, v149
	v_fmamk_f32 v0, v0, 0x3a000000, v202
	v_mul_f32_e32 v149, 0x4f800000, v0
	v_cmp_gt_f32_e32 vcc, s60, v0
	s_nop 1
	v_cndmask_b32_e32 v0, v0, v149, vcc
	v_sqrt_f32_e32 v149, v0
	s_nop 0
	v_add_u32_e32 v150, -1, v149
	v_fma_f32 v151, -v150, v149, v0
	v_cmp_ge_f32_e64 s[36:37], 0, v151
	v_add_u32_e32 v151, 1, v149
	s_nop 0
	v_cndmask_b32_e64 v150, v149, v150, s[36:37]
	v_fma_f32 v149, -v151, v149, v0
	v_cmp_lt_f32_e64 s[36:37], 0, v149
	s_nop 1
	v_cndmask_b32_e64 v149, v150, v151, s[36:37]
	v_mul_f32_e32 v150, 0x37800000, v149
	v_cndmask_b32_e32 v149, v149, v150, vcc
	v_cmp_class_f32_e32 vcc, v0, v203
	s_nop 1
	v_cndmask_b32_e32 v0, v149, v0, vcc
	v_div_scale_f32 v149, s[12:13], v0, v0, 1.0
	v_rcp_f32_e32 v150, v149
	s_nop 0
	v_fma_f32 v151, -v149, v150, 1.0
	v_fmac_f32_e32 v150, v151, v150
	v_div_scale_f32 v151, vcc, 1.0, v0, 1.0
	v_mul_f32_e32 v152, v151, v150
	v_fma_f32 v153, -v149, v152, v151
	v_fmac_f32_e32 v152, v153, v150
	v_fma_f32 v149, -v149, v152, v151
	v_div_fmas_f32 v149, v149, v150, v152
	v_div_fixup_f32 v0, v149, v0, 1.0
	v_pk_mul_f32 v[94:95], v[94:95], v[0:1] op_sel_hi:[1,0]
	v_pk_mul_f32 v[96:97], v[96:97], v[0:1] op_sel_hi:[1,0]
	v_pk_fma_f32 v[94:95], v[2:3], v[94:95], v[6:7]
	v_pk_fma_f32 v[96:97], v[4:5], v[96:97], v[8:9]
	v_bfe_u32 v150, v94, 16, 1
	v_add3_u32 v94, v94, v150, s94
	v_bfe_u32 v150, v95, 16, 1
	v_lshrrev_b32_e32 v94, 16, v94
	v_add3_u32 v95, v95, v150, s94
	v_and_or_b32 v94, v95, s95, v94
	v_bfe_u32 v95, v96, 16, 1
	v_add3_u32 v95, v96, v95, s94
	v_bfe_u32 v96, v97, 16, 1
	v_lshrrev_b32_e32 v95, 16, v95
	v_add3_u32 v96, v97, v96, s94
	v_pk_mul_f32 v[90:91], v[90:91], v[0:1] op_sel_hi:[1,0]
	v_lshlrev_b32_e32 v149, 3, v130
	v_and_or_b32 v95, v96, s95, v95
	v_pk_fma_f32 v[90:91], v[22:23], v[90:91], v[18:19]
	global_store_dwordx2 v149, v[94:95], s[8:9]
	v_bfe_u32 v94, v90, 16, 1
	v_pk_mul_f32 v[92:93], v[92:93], v[0:1] op_sel_hi:[1,0]
	v_add3_u32 v90, v90, v94, s94
	v_bfe_u32 v94, v91, 16, 1
	v_pk_fma_f32 v[92:93], v[24:25], v[92:93], v[20:21]
	v_lshrrev_b32_e32 v90, 16, v90
	v_add3_u32 v91, v91, v94, s94
	v_and_or_b32 v90, v91, s95, v90
	v_bfe_u32 v91, v92, 16, 1
	v_add3_u32 v91, v92, v91, s94
	v_bfe_u32 v92, v93, 16, 1
	v_lshrrev_b32_e32 v91, 16, v91
	v_add3_u32 v92, v93, v92, s94
	v_pk_mul_f32 v[54:55], v[54:55], v[0:1] op_sel_hi:[1,0]
	v_and_or_b32 v91, v92, s95, v91
	v_pk_fma_f32 v[54:55], v[38:39], v[54:55], v[34:35]
	global_store_dwordx2 v149, v[90:91], s[8:9] offset:512
	v_bfe_u32 v90, v54, 16, 1
	v_pk_mul_f32 v[56:57], v[56:57], v[0:1] op_sel_hi:[1,0]
	v_add3_u32 v54, v54, v90, s94
	v_bfe_u32 v90, v55, 16, 1
	v_pk_fma_f32 v[56:57], v[40:41], v[56:57], v[36:37]
	v_lshrrev_b32_e32 v54, 16, v54
	v_add3_u32 v55, v55, v90, s94
	v_and_or_b32 v54, v55, s95, v54
	v_bfe_u32 v55, v56, 16, 1
	v_add3_u32 v55, v56, v55, s94
	v_bfe_u32 v56, v57, 16, 1
	v_lshrrev_b32_e32 v55, 16, v55
	v_add3_u32 v56, v57, v56, s94
	v_pk_mul_f32 v[42:43], v[42:43], v[0:1] op_sel_hi:[1,0]
	v_and_or_b32 v55, v56, s95, v55
	v_pk_fma_f32 v[42:43], v[86:87], v[42:43], v[78:79]
	global_store_dwordx2 v149, v[54:55], s[8:9] offset:1024
	v_bfe_u32 v54, v42, 16, 1
	v_pk_mul_f32 v[44:45], v[44:45], v[0:1] op_sel_hi:[1,0]
	v_add3_u32 v42, v42, v54, s94
	v_bfe_u32 v54, v43, 16, 1
	v_pk_fma_f32 v[44:45], v[88:89], v[44:45], v[80:81]
	v_lshrrev_b32_e32 v42, 16, v42
	v_add3_u32 v43, v43, v54, s94
	v_and_or_b32 v42, v43, s95, v42
	v_bfe_u32 v43, v44, 16, 1
	v_add3_u32 v43, v44, v43, s94
	v_bfe_u32 v44, v45, 16, 1
	v_lshrrev_b32_e32 v43, 16, v43
	v_add3_u32 v44, v45, v44, s94
	v_pk_mul_f32 v[30:31], v[30:31], v[0:1] op_sel_hi:[1,0]
; #define GAS __attribute__((address_space(1)))
; __device__ __forceinline__ unsigned pk2(float lo, float hi) { return f2bf(lo) | (f2bf(hi) << 16); }
; __device__ __forceinline__ void modulate_phase(Frame& F, const float* x, bf16* H, const float* gnorm, const float* modsub) {
;     ...
;         GAS unsigned long long* o8 = (GAS unsigned long long*)(H + (size_t)r * D) + F.lane;
; #pragma unroll
;         for (int j = 0; j < 8; ++j) { const f32x4 y = v[j] * rstd * gs[j] + sh[j];
;             o8[64 * j] = (unsigned long long)pk2(y.x, y.y) | ((unsigned long long)pk2(y.z, y.w) << 32); }
; #pragma unroll
;         for (int j = 0; j < 8; ++j) v[j] = nv[j];
	v_and_or_b32 v43, v44, s95, v43
	v_pk_fma_f32 v[30:31], v[102:103], v[30:31], v[98:99]
	global_store_dwordx2 v149, v[42:43], s[8:9] offset:1536
	v_bfe_u32 v42, v30, 16, 1
	v_pk_mul_f32 v[32:33], v[32:33], v[0:1] op_sel_hi:[1,0]
	v_add3_u32 v30, v30, v42, s94
	v_bfe_u32 v42, v31, 16, 1
	v_pk_fma_f32 v[32:33], v[104:105], v[32:33], v[100:101]
	v_lshrrev_b32_e32 v30, 16, v30
	v_add3_u32 v31, v31, v42, s94
	v_and_or_b32 v30, v31, s95, v30
	v_bfe_u32 v31, v32, 16, 1
	v_add3_u32 v31, v32, v31, s94
	v_bfe_u32 v32, v33, 16, 1
	v_lshrrev_b32_e32 v31, 16, v31
	v_add3_u32 v32, v33, v32, s94
	v_pk_mul_f32 v[26:27], v[26:27], v[0:1] op_sel_hi:[1,0]
	v_and_or_b32 v31, v32, s95, v31
	v_pk_fma_f32 v[26:27], v[110:111], v[26:27], v[106:107]
	global_store_dwordx2 v149, v[30:31], s[8:9] offset:2048
	v_bfe_u32 v30, v26, 16, 1
	v_pk_mul_f32 v[28:29], v[28:29], v[0:1] op_sel_hi:[1,0]
	v_add3_u32 v26, v26, v30, s94
	v_bfe_u32 v30, v27, 16, 1
	v_pk_fma_f32 v[28:29], v[112:113], v[28:29], v[108:109]
	v_lshrrev_b32_e32 v26, 16, v26
	v_add3_u32 v27, v27, v30, s94
	v_and_or_b32 v26, v27, s95, v26
	v_bfe_u32 v27, v28, 16, 1
	v_add3_u32 v27, v28, v27, s94
	v_bfe_u32 v28, v29, 16, 1
	v_lshrrev_b32_e32 v27, 16, v27
	v_add3_u32 v28, v29, v28, s94
	v_pk_mul_f32 v[14:15], v[14:15], v[0:1] op_sel_hi:[1,0]
	v_pk_mul_f32 v[10:11], v[10:11], v[0:1] op_sel_hi:[1,0]
	v_and_or_b32 v27, v28, s95, v27
	v_pk_fma_f32 v[14:15], v[118:119], v[14:15], v[114:115]
	v_pk_fma_f32 v[10:11], v[122:123], v[10:11], v[126:127]
	global_store_dwordx2 v149, v[26:27], s[8:9] offset:2560
	v_pk_mul_f32 v[16:17], v[16:17], v[0:1] op_sel_hi:[1,0]
	v_bfe_u32 v26, v14, 16, 1
	v_pk_mul_f32 v[12:13], v[12:13], v[0:1] op_sel_hi:[1,0]
	v_bfe_u32 v0, v10, 16, 1
	v_add3_u32 v14, v14, v26, s94
	v_bfe_u32 v26, v15, 16, 1
	v_add3_u32 v0, v10, v0, s94
	v_bfe_u32 v10, v11, 16, 1
	v_pk_fma_f32 v[16:17], v[120:121], v[16:17], v[116:117]
	v_lshrrev_b32_e32 v14, 16, v14
	v_add3_u32 v15, v15, v26, s94
	v_pk_fma_f32 v[12:13], v[124:125], v[12:13], v[128:129]
	v_lshrrev_b32_e32 v0, 16, v0
	v_add3_u32 v10, v11, v10, s94
	v_and_or_b32 v14, v15, s95, v14
	v_bfe_u32 v15, v16, 16, 1
	v_and_or_b32 v10, v10, s95, v0
	v_bfe_u32 v0, v12, 16, 1
	v_add3_u32 v15, v16, v15, s94
	v_bfe_u32 v16, v17, 16, 1
	v_add3_u32 v0, v12, v0, s94
	v_bfe_u32 v11, v13, 16, 1
	v_lshrrev_b32_e32 v15, 16, v15
	v_add3_u32 v16, v17, v16, s94
	v_lshrrev_b32_e32 v0, 16, v0
	v_add3_u32 v11, v13, v11, s94
	v_and_or_b32 v15, v16, s95, v15
	v_and_or_b32 v11, v11, s95, v0
	global_store_dwordx2 v149, v[14:15], s[8:9] offset:3072
	global_store_dwordx2 v149, v[10:11], s[8:9] offset:3584
	s_add_u32 s8, s8, 0x1000
	s_addc_u32 s9, s9, 0
	s_cmp_lt_i32 s6, s2
	s_waitcnt vmcnt(8)
	v_mov_b32_e32 v94, v82
	v_mov_b32_e32 v95, v83
	v_mov_b32_e32 v96, v84
	v_mov_b32_e32 v97, v85
	v_mov_b32_e32 v90, v74
	v_mov_b32_e32 v91, v75
	v_mov_b32_e32 v92, v76
	v_mov_b32_e32 v93, v77
	v_mov_b32_e32 v54, v66
	v_mov_b32_e32 v55, v67
	v_mov_b32_e32 v56, v68
	v_mov_b32_e32 v57, v69
	v_mov_b32_e32 v42, v58
	v_mov_b32_e32 v43, v59
	v_mov_b32_e32 v44, v60
	v_mov_b32_e32 v45, v61
	v_mov_b32_e32 v30, v70
	v_mov_b32_e32 v31, v71
	v_mov_b32_e32 v32, v72
	v_mov_b32_e32 v33, v73
	v_mov_b32_e32 v26, v62
	v_mov_b32_e32 v27, v63
	v_mov_b32_e32 v28, v64
	v_mov_b32_e32 v29, v65
	v_mov_b32_e32 v14, v50
	v_mov_b32_e32 v15, v51
	v_mov_b32_e32 v16, v52
	v_mov_b32_e32 v17, v53
	v_mov_b32_e32 v10, v46
	v_mov_b32_e32 v11, v47
	v_mov_b32_e32 v12, v48
	v_mov_b32_e32 v13, v49
	s_cbranch_scc0 .LBB0_219
; #define GAS __attribute__((address_space(1)))
; __device__ __forceinline__ void modulate_phase(Frame& F, const float* x, bf16* H, const float* gnorm, const float* modsub) {
;     ...
;     for (int r = rbeg; r < rend; ++r) {
;         { const GAS f32x4* xn = (const GAS f32x4*)(x + (size_t)min(r + 1, rend - 1) * D) + F.lane;
; #pragma unroll
;           for (int j = 0; j < 8; ++j) nv[j] = xn[64 * j]; }
;         const int b = r >> 12;
;         if (b != curb) { curb = b;
; #pragma unroll
;             for (int j = 0; j < 8; ++j) { const int c = 4 * F.lane + 256 * j;
;                 const f32x4 g = *(const GAS f32x4*)(gnorm + c), sc = *(const GAS f32x4*)(modsub + (size_t)b * NMOD + D + c);
;                 gs[j] = g * (sc + 1.0f); sh[j] = *(const GAS f32x4*)(modsub + (size_t)b * NMOD + c); } }
.LBB0_217:
	s_mov_b32 s7, s6
	s_add_i32 s6, s6, 1
	s_min_i32 s12, s6, s16
	s_ashr_i32 s13, s12, 31
	s_lshl_b64 s[12:13], s[12:13], 13
	s_add_u32 s12, s0, s12
	s_addc_u32 s13, s1, s13
	v_lshlrev_b32_e32 v0, 4, v130
	v_lshl_add_u64 v[46:47], s[12:13], 0, v[0:1]
	v_add_co_u32_e32 v46, vcc, 0x1000, v46
	global_load_dwordx4 v[82:85], v0, s[12:13]
	global_load_dwordx4 v[74:77], v0, s[12:13] offset:1024
	global_load_dwordx4 v[66:69], v0, s[12:13] offset:2048
	global_load_dwordx4 v[58:61], v0, s[12:13] offset:3072
	v_addc_co_u32_e32 v47, vcc, 0, v47, vcc
	global_load_dwordx4 v[70:73], v[46:47], off
	global_load_dwordx4 v[62:65], v[46:47], off offset:1024
	global_load_dwordx4 v[50:53], v[46:47], off offset:2048
	s_nop 0
	global_load_dwordx4 v[46:49], v[46:47], off offset:3072
	s_ashr_i32 s7, s7, 12
	s_cmp_eq_u32 s7, s10
	s_cbranch_scc1 .LBB0_216
	s_mul_i32 s10, s7, 0x12000
	s_mul_hi_i32 s11, s7, 0x12000
	s_add_u32 s10, s14, s10
	s_addc_u32 s11, s15, s11
	s_add_u32 s12, s10, 0x2000
	s_addc_u32 s13, s11, 0
	global_load_dwordx4 v[2:5], v[132:133], off
	global_load_dwordx4 v[6:9], v131, s[12:13]
	s_waitcnt vmcnt(0)
	v_pk_add_f32 v[8:9], v[8:9], 1.0 op_sel_hi:[1,0]
	v_pk_add_f32 v[6:7], v[6:7], 1.0 op_sel_hi:[1,0]
	v_pk_mul_f32 v[4:5], v[4:5], v[8:9]
	v_pk_mul_f32 v[2:3], v[2:3], v[6:7]
	global_load_dwordx4 v[6:9], v131, s[10:11]
	global_load_dwordx4 v[18:21], v[132:133], off offset:1024
	global_load_dwordx4 v[22:25], v142, s[12:13]
	s_waitcnt vmcnt(0)
	v_pk_add_f32 v[24:25], v[24:25], 1.0 op_sel_hi:[1,0]
	v_pk_add_f32 v[22:23], v[22:23], 1.0 op_sel_hi:[1,0]
	v_pk_mul_f32 v[24:25], v[20:21], v[24:25]
	v_pk_mul_f32 v[22:23], v[18:19], v[22:23]
	global_load_dwordx4 v[18:21], v131, s[10:11] offset:1024
	global_load_dwordx4 v[34:37], v[132:133], off offset:2048
	global_load_dwordx4 v[38:41], v143, s[12:13]
	s_waitcnt vmcnt(0)
	v_pk_add_f32 v[40:41], v[40:41], 1.0 op_sel_hi:[1,0]
	v_pk_add_f32 v[38:39], v[38:39], 1.0 op_sel_hi:[1,0]
	v_pk_mul_f32 v[40:41], v[36:37], v[40:41]
	v_pk_mul_f32 v[38:39], v[34:35], v[38:39]
	global_load_dwordx4 v[34:37], v131, s[10:11] offset:2048
	global_load_dwordx4 v[78:81], v[132:133], off offset:3072
	global_load_dwordx4 v[86:89], v144, s[12:13]
	s_waitcnt vmcnt(0)
	v_pk_add_f32 v[88:89], v[88:89], 1.0 op_sel_hi:[1,0]
	v_pk_add_f32 v[86:87], v[86:87], 1.0 op_sel_hi:[1,0]
	v_pk_mul_f32 v[88:89], v[80:81], v[88:89]
	v_pk_mul_f32 v[86:87], v[78:79], v[86:87]
	global_load_dwordx4 v[78:81], v131, s[10:11] offset:3072
	global_load_dwordx4 v[98:101], v[134:135], off
	global_load_dwordx4 v[102:105], v145, s[12:13]
	s_waitcnt vmcnt(0)
	v_pk_add_f32 v[104:105], v[104:105], 1.0 op_sel_hi:[1,0]
	v_pk_add_f32 v[102:103], v[102:103], 1.0 op_sel_hi:[1,0]
	v_pk_mul_f32 v[104:105], v[100:101], v[104:105]
	v_pk_mul_f32 v[102:103], v[98:99], v[102:103]
	global_load_dwordx4 v[98:101], v145, s[10:11]
	global_load_dwordx4 v[106:109], v[136:137], off
	global_load_dwordx4 v[110:113], v146, s[12:13]
	s_waitcnt vmcnt(0)
	v_pk_add_f32 v[112:113], v[112:113], 1.0 op_sel_hi:[1,0]
	v_pk_add_f32 v[110:111], v[110:111], 1.0 op_sel_hi:[1,0]
	v_pk_mul_f32 v[112:113], v[108:109], v[112:113]
	v_pk_mul_f32 v[110:111], v[106:107], v[110:111]
	global_load_dwordx4 v[106:109], v146, s[10:11]
	global_load_dwordx4 v[114:117], v[138:139], off
	global_load_dwordx4 v[118:121], v147, s[12:13]
	s_waitcnt vmcnt(0)
	v_pk_add_f32 v[120:121], v[120:121], 1.0 op_sel_hi:[1,0]
	v_pk_add_f32 v[118:119], v[118:119], 1.0 op_sel_hi:[1,0]
	v_pk_mul_f32 v[120:121], v[116:117], v[120:121]
	v_pk_mul_f32 v[118:119], v[114:115], v[118:119]
	global_load_dwordx4 v[114:117], v147, s[10:11]
	global_load_dwordx4 v[122:125], v[140:141], off
	global_load_dwordx4 v[126:129], v148, s[12:13]
	s_waitcnt vmcnt(0)
	v_pk_add_f32 v[128:129], v[128:129], 1.0 op_sel_hi:[1,0]
	v_pk_add_f32 v[126:127], v[126:127], 1.0 op_sel_hi:[1,0]
	v_pk_mul_f32 v[124:125], v[124:125], v[128:129]
	v_pk_mul_f32 v[122:123], v[122:123], v[126:127]
	global_load_dwordx4 v[126:129], v148, s[10:11]
	s_waitcnt vmcnt(0)
	s_mov_b32 s10, s7
	s_branch .LBB0_216

; #define GAS __attribute__((address_space(1)))
; __device__ __forceinline__ unsigned pk2(float lo, float hi) { return f2bf(lo) | (f2bf(hi) << 16); }
; __device__ __forceinline__ void modulate_phase(Frame& F, const float* x, bf16* H, const float* gnorm, const float* modsub) {
;     ...
;         float s = 0.f;
; #pragma unroll
;         for (int j = 0; j < 8; ++j) s += (v[j].x * v[j].x + v[j].y * v[j].y) + (v[j].z * v[j].z + v[j].w * v[j].w);
;         const float rstd = 1.0f / sqrtf(wave_sum(s) * (1.0f / D) + RMS_EPS);
;         GAS unsigned long long* o8 = (GAS unsigned long long*)(H + (size_t)r * D) + F.lane;
; #pragma unroll
;         for (int j = 0; j < 8; ++j) { const f32x4 y = v[j] * rstd * gs[j] + sh[j];
;             o8[64 * j] = (unsigned long long)pk2(y.x, y.y) | ((unsigned long long)pk2(y.z, y.w) << 32); }
.LBB0_418:
	s_waitcnt vmcnt(8)
	v_mul_f32_e32 v0, v95, v95
	v_mul_f32_e32 v155, v97, v97
	v_fmac_f32_e32 v0, v94, v94
	v_fmac_f32_e32 v155, v96, v96
	v_add_f32_e32 v0, v0, v155
	v_mul_f32_e32 v155, v83, v83
	v_mul_f32_e32 v156, v85, v85
	v_fmac_f32_e32 v155, v82, v82
	v_fmac_f32_e32 v156, v84, v84
	v_add_f32_e32 v155, v155, v156
	v_add_f32_e32 v0, v0, v155
	v_mul_f32_e32 v155, v47, v47
	v_mul_f32_e32 v156, v49, v49
	v_fmac_f32_e32 v155, v46, v46
	v_fmac_f32_e32 v156, v48, v48
	v_add_f32_e32 v155, v155, v156
	v_add_f32_e32 v0, v155, v0
	v_mul_f32_e32 v155, v35, v35
	v_mul_f32_e32 v156, v37, v37
	v_fmac_f32_e32 v155, v34, v34
	v_fmac_f32_e32 v156, v36, v36
	v_add_f32_e32 v155, v155, v156
	v_add_f32_e32 v0, v155, v0
	v_mul_f32_e32 v155, v31, v31
	v_mul_f32_e32 v156, v33, v33
	v_fmac_f32_e32 v155, v30, v30
	v_fmac_f32_e32 v156, v32, v32
	v_add_f32_e32 v155, v155, v156
	v_add_f32_e32 v0, v155, v0
	v_mul_f32_e32 v155, v19, v19
	v_mul_f32_e32 v156, v21, v21
	v_fmac_f32_e32 v155, v18, v18
	v_fmac_f32_e32 v156, v20, v20
	v_add_f32_e32 v155, v155, v156
	v_add_f32_e32 v0, v155, v0
	v_mul_f32_e32 v155, v15, v15
	v_mul_f32_e32 v156, v17, v17
	v_fmac_f32_e32 v155, v14, v14
	v_fmac_f32_e32 v156, v16, v16
	v_add_f32_e32 v155, v155, v156
	v_add_f32_e32 v0, v155, v0
	v_mul_f32_e32 v155, v3, v3
	v_mul_f32_e32 v156, v5, v5
	v_fmac_f32_e32 v155, v2, v2
	v_fmac_f32_e32 v156, v4, v4
	v_add_f32_e32 v155, v155, v156
	v_add_f32_e32 v0, v155, v0
	ds_swizzle_b32 v155, v0 offset:swizzle(SWAP,1)
	s_waitcnt lgkmcnt(0)
	v_add_f32_e32 v0, v0, v155
	ds_swizzle_b32 v155, v0 offset:swizzle(SWAP,2)
	s_waitcnt lgkmcnt(0)
	v_add_f32_e32 v0, v0, v155
	ds_swizzle_b32 v155, v0 offset:swizzle(SWAP,4)
	s_waitcnt lgkmcnt(0)
	v_add_f32_e32 v0, v0, v155
	ds_swizzle_b32 v155, v0 offset:swizzle(SWAP,8)
	s_waitcnt lgkmcnt(0)
	v_add_f32_e32 v0, v0, v155
	ds_swizzle_b32 v155, v0 offset:swizzle(SWAP,16)
	s_waitcnt lgkmcnt(0)
	v_add_f32_e32 v0, v0, v155
	v_mov_b32_e32 v155, v0
	s_nop 1
	v_permlane32_swap_b32_e32 v0, v155
	v_add_f32_e32 v0, v0, v155
	v_fmamk_f32 v0, v0, 0x3a000000, v202
	v_mul_f32_e32 v155, 0x4f800000, v0
	v_cmp_gt_f32_e32 vcc, s60, v0
	s_nop 1
	v_cndmask_b32_e32 v0, v0, v155, vcc
	v_sqrt_f32_e32 v155, v0
	s_nop 0
	v_add_u32_e32 v156, -1, v155
	v_fma_f32 v157, -v156, v155, v0
	v_cmp_ge_f32_e64 s[38:39], 0, v157
	v_add_u32_e32 v157, 1, v155
	s_nop 0
	v_cndmask_b32_e64 v156, v155, v156, s[38:39]
	v_fma_f32 v155, -v157, v155, v0
	v_cmp_lt_f32_e64 s[38:39], 0, v155
	s_nop 1
	v_cndmask_b32_e64 v155, v156, v157, s[38:39]
	v_mul_f32_e32 v156, 0x37800000, v155
	v_cndmask_b32_e32 v155, v155, v156, vcc
	v_cmp_class_f32_e32 vcc, v0, v203
	s_nop 1
	v_cndmask_b32_e32 v0, v155, v0, vcc
	v_div_scale_f32 v155, s[10:11], v0, v0, 1.0
	v_rcp_f32_e32 v156, v155
	s_nop 0
	v_fma_f32 v157, -v155, v156, 1.0
	v_fmac_f32_e32 v156, v157, v156
	v_div_scale_f32 v157, vcc, 1.0, v0, 1.0
	v_mul_f32_e32 v158, v157, v156
	v_fma_f32 v159, -v155, v158, v157
	v_fmac_f32_e32 v158, v159, v156
	v_fma_f32 v155, -v155, v158, v157
	v_div_fmas_f32 v155, v155, v156, v158
	v_div_fixup_f32 v0, v155, v0, 1.0
	v_pk_mul_f32 v[94:95], v[94:95], v[0:1] op_sel_hi:[1,0]
	v_pk_mul_f32 v[96:97], v[96:97], v[0:1] op_sel_hi:[1,0]
	v_pk_fma_f32 v[94:95], v[6:7], v[94:95], v[10:11]
	v_pk_fma_f32 v[96:97], v[8:9], v[96:97], v[12:13]
	v_bfe_u32 v156, v94, 16, 1
	v_add3_u32 v94, v94, v156, s94
	v_bfe_u32 v156, v95, 16, 1
	v_lshrrev_b32_e32 v94, 16, v94
	v_add3_u32 v95, v95, v156, s94
	v_and_or_b32 v94, v95, s95, v94
	v_bfe_u32 v95, v96, 16, 1
	v_add3_u32 v95, v96, v95, s94
	v_bfe_u32 v96, v97, 16, 1
	v_lshrrev_b32_e32 v95, 16, v95
	v_add3_u32 v96, v97, v96, s94
	v_pk_mul_f32 v[82:83], v[82:83], v[0:1] op_sel_hi:[1,0]
	v_lshlrev_b32_e32 v155, 3, v130
	v_and_or_b32 v95, v96, s95, v95
	v_pk_fma_f32 v[82:83], v[26:27], v[82:83], v[22:23]
	global_store_dwordx2 v155, v[94:95], s[6:7]
	v_bfe_u32 v94, v82, 16, 1
	v_pk_mul_f32 v[84:85], v[84:85], v[0:1] op_sel_hi:[1,0]
	v_add3_u32 v82, v82, v94, s94
	v_bfe_u32 v94, v83, 16, 1
	v_pk_fma_f32 v[84:85], v[28:29], v[84:85], v[24:25]
	v_lshrrev_b32_e32 v82, 16, v82
	v_add3_u32 v83, v83, v94, s94
	v_and_or_b32 v82, v83, s95, v82
	v_bfe_u32 v83, v84, 16, 1
	v_add3_u32 v83, v84, v83, s94
	v_bfe_u32 v84, v85, 16, 1
	v_lshrrev_b32_e32 v83, 16, v83
	v_add3_u32 v84, v85, v84, s94
	v_pk_mul_f32 v[46:47], v[46:47], v[0:1] op_sel_hi:[1,0]
	v_and_or_b32 v83, v84, s95, v83
	v_pk_fma_f32 v[46:47], v[42:43], v[46:47], v[38:39]
	global_store_dwordx2 v155, v[82:83], s[6:7] offset:512
	v_bfe_u32 v82, v46, 16, 1
	v_pk_mul_f32 v[48:49], v[48:49], v[0:1] op_sel_hi:[1,0]
	v_add3_u32 v46, v46, v82, s94
	v_bfe_u32 v82, v47, 16, 1
	v_pk_fma_f32 v[48:49], v[44:45], v[48:49], v[40:41]
	v_lshrrev_b32_e32 v46, 16, v46
	v_add3_u32 v47, v47, v82, s94
	v_and_or_b32 v46, v47, s95, v46
	v_bfe_u32 v47, v48, 16, 1
	v_add3_u32 v47, v48, v47, s94
	v_bfe_u32 v48, v49, 16, 1
	v_lshrrev_b32_e32 v47, 16, v47
	v_add3_u32 v48, v49, v48, s94
	v_pk_mul_f32 v[34:35], v[34:35], v[0:1] op_sel_hi:[1,0]
	v_and_or_b32 v47, v48, s95, v47
	v_pk_fma_f32 v[34:35], v[90:91], v[34:35], v[78:79]
	global_store_dwordx2 v155, v[46:47], s[6:7] offset:1024
	v_bfe_u32 v46, v34, 16, 1
	v_pk_mul_f32 v[36:37], v[36:37], v[0:1] op_sel_hi:[1,0]
	v_add3_u32 v34, v34, v46, s94
	v_bfe_u32 v46, v35, 16, 1
	v_pk_fma_f32 v[36:37], v[92:93], v[36:37], v[80:81]
	v_lshrrev_b32_e32 v34, 16, v34
	v_add3_u32 v35, v35, v46, s94
	v_and_or_b32 v34, v35, s95, v34
	v_bfe_u32 v35, v36, 16, 1
	v_add3_u32 v35, v36, v35, s94
	v_bfe_u32 v36, v37, 16, 1
	v_lshrrev_b32_e32 v35, 16, v35
	v_add3_u32 v36, v37, v36, s94
	v_pk_mul_f32 v[30:31], v[30:31], v[0:1] op_sel_hi:[1,0]
	v_and_or_b32 v35, v36, s95, v35
; #define GAS __attribute__((address_space(1)))
; __device__ __forceinline__ unsigned pk2(float lo, float hi) { return f2bf(lo) | (f2bf(hi) << 16); }
; __device__ __forceinline__ void modulate_phase(Frame& F, const float* x, bf16* H, const float* gnorm, const float* modsub) {
;     ...
;         GAS unsigned long long* o8 = (GAS unsigned long long*)(H + (size_t)r * D) + F.lane;
; #pragma unroll
;         for (int j = 0; j < 8; ++j) { const f32x4 y = v[j] * rstd * gs[j] + sh[j];
;             o8[64 * j] = (unsigned long long)pk2(y.x, y.y) | ((unsigned long long)pk2(y.z, y.w) << 32); }
; #pragma unroll
;         for (int j = 0; j < 8; ++j) v[j] = nv[j];
	v_pk_fma_f32 v[30:31], v[102:103], v[30:31], v[98:99]
	global_store_dwordx2 v155, v[34:35], s[6:7] offset:1536
	v_bfe_u32 v34, v30, 16, 1
	v_pk_mul_f32 v[32:33], v[32:33], v[0:1] op_sel_hi:[1,0]
	v_add3_u32 v30, v30, v34, s94
	v_bfe_u32 v34, v31, 16, 1
	v_pk_fma_f32 v[32:33], v[104:105], v[32:33], v[100:101]
	v_lshrrev_b32_e32 v30, 16, v30
	v_add3_u32 v31, v31, v34, s94
	v_and_or_b32 v30, v31, s95, v30
	v_bfe_u32 v31, v32, 16, 1
	v_add3_u32 v31, v32, v31, s94
	v_bfe_u32 v32, v33, 16, 1
	v_lshrrev_b32_e32 v31, 16, v31
	v_add3_u32 v32, v33, v32, s94
	v_pk_mul_f32 v[18:19], v[18:19], v[0:1] op_sel_hi:[1,0]
	v_and_or_b32 v31, v32, s95, v31
	v_pk_fma_f32 v[18:19], v[110:111], v[18:19], v[106:107]
	global_store_dwordx2 v155, v[30:31], s[6:7] offset:2048
	v_bfe_u32 v30, v18, 16, 1
	v_pk_mul_f32 v[20:21], v[20:21], v[0:1] op_sel_hi:[1,0]
	v_add3_u32 v18, v18, v30, s94
	v_bfe_u32 v30, v19, 16, 1
	v_pk_fma_f32 v[20:21], v[112:113], v[20:21], v[108:109]
	v_lshrrev_b32_e32 v18, 16, v18
	v_add3_u32 v19, v19, v30, s94
	v_and_or_b32 v18, v19, s95, v18
	v_bfe_u32 v19, v20, 16, 1
	v_add3_u32 v19, v20, v19, s94
	v_bfe_u32 v20, v21, 16, 1
	v_lshrrev_b32_e32 v19, 16, v19
	v_add3_u32 v20, v21, v20, s94
	v_pk_mul_f32 v[14:15], v[14:15], v[0:1] op_sel_hi:[1,0]
	v_pk_mul_f32 v[2:3], v[2:3], v[0:1] op_sel_hi:[1,0]
	v_and_or_b32 v19, v20, s95, v19
	v_pk_fma_f32 v[14:15], v[118:119], v[14:15], v[114:115]
	v_pk_fma_f32 v[2:3], v[122:123], v[2:3], v[126:127]
	global_store_dwordx2 v155, v[18:19], s[6:7] offset:2560
	v_pk_mul_f32 v[16:17], v[16:17], v[0:1] op_sel_hi:[1,0]
	v_bfe_u32 v18, v14, 16, 1
	v_pk_mul_f32 v[4:5], v[4:5], v[0:1] op_sel_hi:[1,0]
	v_bfe_u32 v0, v2, 16, 1
	v_add3_u32 v14, v14, v18, s94
	v_bfe_u32 v18, v15, 16, 1
	v_add3_u32 v0, v2, v0, s94
	v_bfe_u32 v2, v3, 16, 1
	v_pk_fma_f32 v[16:17], v[120:121], v[16:17], v[116:117]
	v_lshrrev_b32_e32 v14, 16, v14
	v_add3_u32 v15, v15, v18, s94
	v_pk_fma_f32 v[4:5], v[124:125], v[4:5], v[128:129]
	v_lshrrev_b32_e32 v0, 16, v0
	v_add3_u32 v2, v3, v2, s94
	v_and_or_b32 v14, v15, s95, v14
	v_bfe_u32 v15, v16, 16, 1
	v_and_or_b32 v2, v2, s95, v0
	v_bfe_u32 v0, v4, 16, 1
	v_add3_u32 v15, v16, v15, s94
	v_bfe_u32 v16, v17, 16, 1
	v_add3_u32 v0, v4, v0, s94
	v_bfe_u32 v3, v5, 16, 1
	v_lshrrev_b32_e32 v15, 16, v15
	v_add3_u32 v16, v17, v16, s94
	v_lshrrev_b32_e32 v0, 16, v0
	v_add3_u32 v3, v5, v3, s94
	v_and_or_b32 v15, v16, s95, v15
	v_and_or_b32 v3, v3, s95, v0
	global_store_dwordx2 v155, v[14:15], s[6:7] offset:3072
	global_store_dwordx2 v155, v[2:3], s[6:7] offset:3584
	s_add_u32 s6, s6, 0x1000
	s_addc_u32 s7, s7, 0
	s_cmp_lt_i32 s0, s2
	s_waitcnt vmcnt(8)
	v_mov_b32_e32 v94, v86
	v_mov_b32_e32 v95, v87
	v_mov_b32_e32 v96, v88
	v_mov_b32_e32 v97, v89
	v_mov_b32_e32 v82, v74
	v_mov_b32_e32 v83, v75
	v_mov_b32_e32 v84, v76
	v_mov_b32_e32 v85, v77
	v_mov_b32_e32 v46, v66
	v_mov_b32_e32 v47, v67
	v_mov_b32_e32 v48, v68
	v_mov_b32_e32 v49, v69
	v_mov_b32_e32 v34, v58
	v_mov_b32_e32 v35, v59
	v_mov_b32_e32 v36, v60
	v_mov_b32_e32 v37, v61
	v_mov_b32_e32 v30, v70
	v_mov_b32_e32 v31, v71
	v_mov_b32_e32 v32, v72
	v_mov_b32_e32 v33, v73
	v_mov_b32_e32 v18, v62
	v_mov_b32_e32 v19, v63
	v_mov_b32_e32 v20, v64
	v_mov_b32_e32 v21, v65
	v_mov_b32_e32 v14, v54
	v_mov_b32_e32 v15, v55
	v_mov_b32_e32 v16, v56
	v_mov_b32_e32 v17, v57
	v_mov_b32_e32 v2, v50
	v_mov_b32_e32 v3, v51
	v_mov_b32_e32 v4, v52
	v_mov_b32_e32 v5, v53
	s_cbranch_scc0 .LBB0_421
; #define GAS __attribute__((address_space(1)))
; __device__ __forceinline__ void modulate_phase(Frame& F, const float* x, bf16* H, const float* gnorm, const float* modsub) {
;     ...
;     for (int r = rbeg; r < rend; ++r) {
;         { const GAS f32x4* xn = (const GAS f32x4*)(x + (size_t)min(r + 1, rend - 1) * D) + F.lane;
; #pragma unroll
;           for (int j = 0; j < 8; ++j) nv[j] = xn[64 * j]; }
;         const int b = r >> 12;
;         if (b != curb) { curb = b;
; #pragma unroll
;             for (int j = 0; j < 8; ++j) { const int c = 4 * F.lane + 256 * j;
;                 const f32x4 g = *(const GAS f32x4*)(gnorm + c), sc = *(const GAS f32x4*)(modsub + (size_t)b * NMOD + D + c);
;                 gs[j] = g * (sc + 1.0f); sh[j] = *(const GAS f32x4*)(modsub + (size_t)b * NMOD + c); } }
.LBB0_419:
	s_mov_b32 s1, s0
	s_add_i32 s0, s0, 1
	s_min_i32 s10, s0, s16
	s_ashr_i32 s11, s10, 31
	s_lshl_b64 s[10:11], s[10:11], 13
	s_add_u32 s10, s12, s10
	s_addc_u32 s11, s13, s11
	v_lshlrev_b32_e32 v0, 4, v130
	v_lshl_add_u64 v[50:51], s[10:11], 0, v[0:1]
	v_add_co_u32_e32 v50, vcc, 0x1000, v50
	global_load_dwordx4 v[86:89], v0, s[10:11]
	global_load_dwordx4 v[74:77], v0, s[10:11] offset:1024
	global_load_dwordx4 v[66:69], v0, s[10:11] offset:2048
	global_load_dwordx4 v[58:61], v0, s[10:11] offset:3072
	v_addc_co_u32_e32 v51, vcc, 0, v51, vcc
	global_load_dwordx4 v[70:73], v[50:51], off
	global_load_dwordx4 v[62:65], v[50:51], off offset:1024
	global_load_dwordx4 v[54:57], v[50:51], off offset:2048
	s_nop 0
	global_load_dwordx4 v[50:53], v[50:51], off offset:3072
	s_ashr_i32 s1, s1, 12
	s_cmp_eq_u32 s1, s8
	s_cbranch_scc1 .LBB0_418
	s_mul_i32 s8, s1, 0x12000
	s_mul_hi_i32 s9, s1, 0x12000
	s_add_u32 s8, s14, s8
	s_addc_u32 s9, s15, s9
	s_add_u32 s10, s8, 0x2000
	s_addc_u32 s11, s9, 0
	global_load_dwordx4 v[6:9], v[132:133], off
	global_load_dwordx4 v[10:13], v131, s[10:11]
	s_waitcnt vmcnt(0)
	v_pk_add_f32 v[12:13], v[12:13], 1.0 op_sel_hi:[1,0]
	v_pk_add_f32 v[10:11], v[10:11], 1.0 op_sel_hi:[1,0]
	v_pk_mul_f32 v[8:9], v[8:9], v[12:13]
	v_pk_mul_f32 v[6:7], v[6:7], v[10:11]
	global_load_dwordx4 v[10:13], v131, s[8:9]
	global_load_dwordx4 v[22:25], v[134:135], off
	global_load_dwordx4 v[26:29], v148, s[10:11]
	s_waitcnt vmcnt(0)
	v_pk_add_f32 v[28:29], v[28:29], 1.0 op_sel_hi:[1,0]
	v_pk_add_f32 v[26:27], v[26:27], 1.0 op_sel_hi:[1,0]
	v_pk_mul_f32 v[28:29], v[24:25], v[28:29]
	v_pk_mul_f32 v[26:27], v[22:23], v[26:27]
	global_load_dwordx4 v[22:25], v131, s[8:9] offset:1024
	global_load_dwordx4 v[38:41], v[136:137], off
	global_load_dwordx4 v[42:45], v149, s[10:11]
	s_waitcnt vmcnt(0)
	v_pk_add_f32 v[44:45], v[44:45], 1.0 op_sel_hi:[1,0]
	v_pk_add_f32 v[42:43], v[42:43], 1.0 op_sel_hi:[1,0]
	v_pk_mul_f32 v[44:45], v[40:41], v[44:45]
	v_pk_mul_f32 v[42:43], v[38:39], v[42:43]
	global_load_dwordx4 v[38:41], v131, s[8:9] offset:2048
	global_load_dwordx4 v[78:81], v[138:139], off
	global_load_dwordx4 v[90:93], v150, s[10:11]
	s_waitcnt vmcnt(0)
	v_pk_add_f32 v[92:93], v[92:93], 1.0 op_sel_hi:[1,0]
	v_pk_add_f32 v[90:91], v[90:91], 1.0 op_sel_hi:[1,0]
	v_pk_mul_f32 v[92:93], v[80:81], v[92:93]
	v_pk_mul_f32 v[90:91], v[78:79], v[90:91]
	global_load_dwordx4 v[78:81], v131, s[8:9] offset:3072
	global_load_dwordx4 v[98:101], v[140:141], off
	global_load_dwordx4 v[102:105], v151, s[10:11]
	s_waitcnt vmcnt(0)
	v_pk_add_f32 v[104:105], v[104:105], 1.0 op_sel_hi:[1,0]
	v_pk_add_f32 v[102:103], v[102:103], 1.0 op_sel_hi:[1,0]
	v_pk_mul_f32 v[104:105], v[100:101], v[104:105]
	v_pk_mul_f32 v[102:103], v[98:99], v[102:103]
	global_load_dwordx4 v[98:101], v151, s[8:9]
	global_load_dwordx4 v[106:109], v[142:143], off
	global_load_dwordx4 v[110:113], v152, s[10:11]
	s_waitcnt vmcnt(0)
	v_pk_add_f32 v[112:113], v[112:113], 1.0 op_sel_hi:[1,0]
	v_pk_add_f32 v[110:111], v[110:111], 1.0 op_sel_hi:[1,0]
	v_pk_mul_f32 v[112:113], v[108:109], v[112:113]
	v_pk_mul_f32 v[110:111], v[106:107], v[110:111]
	global_load_dwordx4 v[106:109], v152, s[8:9]
	global_load_dwordx4 v[114:117], v[144:145], off
	global_load_dwordx4 v[118:121], v153, s[10:11]
	s_waitcnt vmcnt(0)
	v_pk_add_f32 v[120:121], v[120:121], 1.0 op_sel_hi:[1,0]
	v_pk_add_f32 v[118:119], v[118:119], 1.0 op_sel_hi:[1,0]
	v_pk_mul_f32 v[120:121], v[116:117], v[120:121]
	v_pk_mul_f32 v[118:119], v[114:115], v[118:119]
	global_load_dwordx4 v[114:117], v153, s[8:9]
	global_load_dwordx4 v[122:125], v[146:147], off
	global_load_dwordx4 v[126:129], v154, s[10:11]
	s_waitcnt vmcnt(0)
	v_pk_add_f32 v[128:129], v[128:129], 1.0 op_sel_hi:[1,0]
	v_pk_add_f32 v[126:127], v[126:127], 1.0 op_sel_hi:[1,0]
	v_pk_mul_f32 v[124:125], v[124:125], v[128:129]
	v_pk_mul_f32 v[122:123], v[122:123], v[126:127]
	global_load_dwordx4 v[126:129], v154, s[8:9]
	s_waitcnt vmcnt(0)
	s_mov_b32 s8, s1
	s_branch .LBB0_418
